# v72 + grid barrier: waiting workgroups poll their per-XCD release word without the 64-clock sleep between polls
# speedup vs baseline: 1.0095x; 1.0095x over previous
; __device__ __forceinline__ unsigned xb_ld(unsigned* p)              { return __hip_atomic_load(p, __ATOMIC_RELAXED, __HIP_MEMORY_SCOPE_AGENT); }
; #define XB_SPIN(cond, bar) do { unsigned _sp = 0; while (cond) { __builtin_amdgcn_s_sleep(1); \
;     if ((++_sp & 255u) == 0u) { if (xb_ld(&(bar)[XB_TMO])) break; if (_sp > XB_SPIN_CAP) { atomicAdd(&(bar)[XB_TMO], 1u); break; } } } } while (0)
; __device__ __forceinline__ void xcd_barrier(const XcdBarrier& b) {
;     ...
;             XB_SPIN(xb_ld(&bar[XB_XGEN(b.x)]) == gen, bar);
.LBB0_220:
	s_and_b32 s5, s4, 0xff
	s_mov_b64 s[20:21], -1
	s_cmp_lg_u32 s5, 0
	s_mov_b64 s[24:25], -1
	s_nop 0
	s_cbranch_scc0 .LBB0_223
	s_and_b64 vcc, exec, s[24:25]
	s_cbranch_vccz .LBB0_219

; __device__ __forceinline__ unsigned xb_ld(unsigned* p)              { return __hip_atomic_load(p, __ATOMIC_RELAXED, __HIP_MEMORY_SCOPE_AGENT); }
; #define XB_SPIN(cond, bar) do { unsigned _sp = 0; while (cond) { __builtin_amdgcn_s_sleep(1); \
;     if ((++_sp & 255u) == 0u) { if (xb_ld(&(bar)[XB_TMO])) break; if (_sp > XB_SPIN_CAP) { atomicAdd(&(bar)[XB_TMO], 1u); break; } } } } while (0)
; __device__ __forceinline__ void xcd_barrier(const XcdBarrier& b) {
;     ...
;             XB_SPIN(xb_ld(&bar[XB_XGEN(b.x)]) == gen, bar);
.LBB0_314:
	s_and_b32 s4, s2, 0xff
	s_mov_b64 s[20:21], -1
	s_cmp_lg_u32 s4, 0
	s_mov_b64 s[24:25], -1
	s_nop 0
	s_cbranch_scc0 .LBB0_317
	s_and_b64 vcc, exec, s[24:25]
	s_cbranch_vccz .LBB0_313

; __device__ __forceinline__ unsigned xb_ld(unsigned* p)              { return __hip_atomic_load(p, __ATOMIC_RELAXED, __HIP_MEMORY_SCOPE_AGENT); }
; #define XB_SPIN(cond, bar) do { unsigned _sp = 0; while (cond) { __builtin_amdgcn_s_sleep(1); \
;     if ((++_sp & 255u) == 0u) { if (xb_ld(&(bar)[XB_TMO])) break; if (_sp > XB_SPIN_CAP) { atomicAdd(&(bar)[XB_TMO], 1u); break; } } } } while (0)
; __device__ __forceinline__ void xcd_barrier(const XcdBarrier& b) {
;     ...
;             XB_SPIN(xb_ld(&bar[XB_XGEN(b.x)]) == gen, bar);
.LBB0_577:
	s_and_b32 s5, s4, 0xff
	s_mov_b64 s[18:19], -1
	s_cmp_lg_u32 s5, 0
	s_mov_b64 s[22:23], -1
	s_nop 0
	s_cbranch_scc0 .LBB0_580
	s_and_b64 vcc, exec, s[22:23]
	s_cbranch_vccz .LBB0_576

; __device__ __forceinline__ unsigned xb_ld(unsigned* p)              { return __hip_atomic_load(p, __ATOMIC_RELAXED, __HIP_MEMORY_SCOPE_AGENT); }
; #define XB_SPIN(cond, bar) do { unsigned _sp = 0; while (cond) { __builtin_amdgcn_s_sleep(1); \
;     if ((++_sp & 255u) == 0u) { if (xb_ld(&(bar)[XB_TMO])) break; if (_sp > XB_SPIN_CAP) { atomicAdd(&(bar)[XB_TMO], 1u); break; } } } } while (0)
; __device__ __forceinline__ void xcd_barrier(const XcdBarrier& b) {
;     ...
;             XB_SPIN(xb_ld(&bar[XB_XGEN(b.x)]) == gen, bar);
.LBB0_1282:
	s_and_b32 s20, s24, 0xff
	s_mov_b64 s[18:19], -1
	s_cmp_lg_u32 s20, 0
	s_mov_b64 s[22:23], -1
	s_nop 0
	s_cbranch_scc0 .LBB0_1285
	s_and_b64 vcc, exec, s[22:23]
	s_cbranch_vccz .LBB0_1281

; __device__ __forceinline__ unsigned xb_ld(unsigned* p)              { return __hip_atomic_load(p, __ATOMIC_RELAXED, __HIP_MEMORY_SCOPE_AGENT); }
; #define XB_SPIN(cond, bar) do { unsigned _sp = 0; while (cond) { __builtin_amdgcn_s_sleep(1); \
;     if ((++_sp & 255u) == 0u) { if (xb_ld(&(bar)[XB_TMO])) break; if (_sp > XB_SPIN_CAP) { atomicAdd(&(bar)[XB_TMO], 1u); break; } } } } while (0)
; __device__ __forceinline__ void xcd_barrier(const XcdBarrier& b) {
;     ...
;             XB_SPIN(xb_ld(&bar[XB_XGEN(b.x)]) == gen, bar);
.LBB0_1406:
	s_and_b32 s20, s2, 0xff
	s_mov_b64 s[18:19], -1
	s_cmp_lg_u32 s20, 0
	s_mov_b64 s[22:23], -1
	s_nop 0
	s_cbranch_scc0 .LBB0_1409
	s_and_b64 vcc, exec, s[22:23]
	s_cbranch_vccz .LBB0_1405
